# conversion sites at out2/in3/out3 starts use all idle blocks (32../96../32..), 4 items per wave (7168/5120/7168 items); topk3 left with 9984
# speedup vs baseline: 1.0094x; 1.0094x over previous
.LBB0_2131:
	s_cmp_gt_i32 s60, 30
	s_cselect_b64 s[4:5], -1, 0
	s_cmp_lt_i32 s61, 31
	s_cselect_b64 s[6:7], -1, 0
	s_or_b64 s[4:5], s[4:5], s[6:7]
	s_and_b64 vcc, exec, s[4:5]
	s_cbranch_vccnz .LBB0_2207
	v_writelane_b32 v129, s3, 0
	v_writelane_b32 v129, s4, 1
	v_writelane_b32 v129, s5, 2
	v_writelane_b32 v129, s6, 3
	v_writelane_b32 v129, s7, 4
	v_writelane_b32 v129, s8, 5
	v_writelane_b32 v129, s9, 6
	v_writelane_b32 v129, s10, 7
	v_writelane_b32 v129, s11, 8
	v_writelane_b32 v129, s12, 9
	v_writelane_b32 v129, s13, 10
	v_writelane_b32 v129, s14, 11
	v_writelane_b32 v129, s15, 12
	v_writelane_b32 v129, s16, 13
	v_writelane_b32 v129, s17, 14
	v_writelane_b32 v129, s18, 15
	v_writelane_b32 v129, s19, 16
	v_writelane_b32 v129, s20, 17
	v_writelane_b32 v129, s21, 18
	v_writelane_b32 v129, s22, 19
	v_writelane_b32 v129, s23, 20
	v_writelane_b32 v129, s24, 21
	v_writelane_b32 v129, s25, 22
	v_writelane_b32 v129, s26, 23
	v_writelane_b32 v129, s27, 24
	v_writelane_b32 v129, s28, 25
	v_writelane_b32 v129, s29, 26
	v_writelane_b32 v129, s30, 27
	v_writelane_b32 v129, s31, 28
	v_writelane_b32 v129, s33, 29
	v_writelane_b32 v129, s34, 30
	v_writelane_b32 v129, s35, 31
	v_writelane_b32 v129, s36, 32
	v_writelane_b32 v129, s37, 33
	v_writelane_b32 v129, s38, 34
	v_writelane_b32 v129, s39, 35
	v_writelane_b32 v129, s41, 36
	v_writelane_b32 v129, s42, 37
	v_writelane_b32 v129, s43, 38
	v_writelane_b32 v129, s45, 39
	v_writelane_b32 v129, s46, 40
	v_writelane_b32 v129, s47, 41
	v_writelane_b32 v129, s49, 42
	v_writelane_b32 v129, s57, 43
	v_writelane_b32 v129, s58, 44
	v_writelane_b32 v129, s59, 45
	v_writelane_b32 v129, s72, 46
	v_writelane_b32 v129, s73, 47
	v_writelane_b32 v129, s76, 48
	v_writelane_b32 v129, s77, 49
	v_writelane_b32 v129, s78, 50
	v_writelane_b32 v129, s79, 51
	v_writelane_b32 v129, s80, 52
	v_writelane_b32 v129, s81, 53
	v_writelane_b32 v129, s84, 54
	v_writelane_b32 v129, s85, 55
	v_writelane_b32 v129, s86, 56
	v_writelane_b32 v129, s87, 57
	v_writelane_b32 v129, s88, 58
	v_writelane_b32 v129, s89, 59
	v_writelane_b32 v129, s90, 60
	v_writelane_b32 v129, s91, 61
	v_writelane_b32 v129, s92, 62
	v_writelane_b32 v129, s93, 63
	s_cmpk_lt_u32 s2, 0x20
	s_cselect_b64 s[4:5], -1, 0
	s_cmpk_gt_u32 s2, 0x1f
	s_cselect_b64 s[10:11], -1, 0
	s_mov_b32 s3, 0x10d00
	s_and_b64 s[6:7], s[10:11], exec
	s_cselect_b32 s12, s3, 0x12900
	s_mov_b32 s3, 0x12900
	s_cselect_b32 s13, 0x12900, s3
	s_add_i32 s14, s54, 0xc000
	s_cmpk_eq_i32 s56, 0x100
	s_cselect_b64 s[6:7], -1, 0
	s_and_b64 s[8:9], s[6:7], exec
	s_cselect_b32 s18, s13, 0
	s_cselect_b32 s19, s12, s14
	s_mov_b32 s3, 0xc000
	s_cmp_ge_u32 s19, s18
	s_mov_b32 s20, 0x12000
	s_waitcnt vmcnt(0)
	s_barrier
	s_cbranch_scc1 .Lcq1_end
	v_readlane_b32 s8, v255, 7
	s_sub_i32 s8, s8, 0x100
	v_readlane_b32 s13, v255, 6
	s_add_i32 s21, s13, s8
	s_lshl_b32 s22, s21, 1
	s_movk_i32 s12, 0xe00
	s_and_b64 s[8:9], s[10:11], exec
	s_cselect_b32 s12, s12, 0x400
	s_and_b64 s[8:9], s[6:7], exec
	s_mul_i32 s8, s13, 0x2200
	s_cselect_b32 s23, s12, s55
	s_add_i32 s25, s8, 0
	v_cndmask_b32_e64 v2, 0, 1, s[4:5]
	v_and_b32_e32 v1, 63, v0
	s_mov_b32 s9, 0
	s_mov_b32 s24, 0x10000
	s_add_i32 s25, s25, 0x10000
	s_and_b64 s[10:11], s[10:11], s[6:7]
	v_cmp_ne_u32_e64 s[4:5], 1, v2
	v_mov_b32_e32 v3, 0
	s_movk_i32 s26, 0x2000
	s_movk_i32 s27, 0x4000
	s_movk_i32 s28, 0x6000
	s_mov_b32 s29, 0x8000
	s_mov_b32 s30, 0xa000
	s_mov_b32 s31, 0xe000
	s_mov_b32 s34, 0x14000
	s_mov_b32 s35, 0x16000
	s_mov_b32 s36, 0x18000
	s_mov_b32 s37, 0x1a000
	s_mov_b32 s38, 0x1c000
	s_mov_b32 s39, 0x1e000
	s_mov_b32 s41, 0x20000
	s_mov_b32 s42, 0x22000
	s_mov_b32 s43, 0x24000
	s_mov_b32 s45, 0x26000
	s_mov_b32 s46, 0x28000
	s_mov_b32 s47, 0x2a000
	s_mov_b32 s49, 0x2c000
	s_mov_b32 s57, 0x2e000
	s_mov_b32 s58, 0x30000
	s_mov_b32 s59, 0x32000
	s_mov_b32 s72, 0x34000
	s_mov_b32 s73, 0x36000
	s_mov_b32 s78, 0x38000
	s_mov_b32 s79, 0x3a000
	s_mov_b32 s84, 0x3c000
	s_mov_b32 s85, 0x3e000
	s_movk_i32 s86, 0x84
	s_branch .Lcq1_2352

.LBB0_2349:
	s_cmpk_lt_u32 s2, 0x80
	s_cselect_b64 s[4:5], -1, 0
	s_cmpk_gt_u32 s2, 0x7f
	s_cselect_b64 s[10:11], -1, 0
	s_mov_b32 s3, 0x12900
	s_and_b64 s[6:7], s[10:11], exec
	s_cselect_b32 s12, s3, 0x12900
	s_mov_b32 s3, 0x12900
	s_cselect_b32 s13, 0x12900, s3
	s_add_i32 s14, s54, 0xc000
	s_cmpk_eq_i32 s56, 0x100
	s_cselect_b64 s[6:7], -1, 0
	s_and_b64 s[8:9], s[6:7], exec
	s_cselect_b32 s18, s13, 0x12000
	s_cselect_b32 s19, s12, s14
	s_mov_b32 s3, 0xc000
	s_cmp_ge_u32 s19, s18
	s_mov_b32 s20, 0x12000
	s_waitcnt vmcnt(0)
	s_barrier
	s_cbranch_scc1 .LBB0_2364
	v_readlane_b32 s8, v255, 7
	s_and_b32 s8, s8, 0x3f8
	v_readlane_b32 s13, v255, 6
	s_add_i32 s21, s13, s8
	s_lshl_b32 s22, s21, 1
	s_movk_i32 s12, 0x800
	s_and_b64 s[8:9], s[10:11], exec
	s_cselect_b32 s12, s12, 0x400
	s_and_b64 s[8:9], s[6:7], exec
	s_mul_i32 s8, s13, 0x2200
	s_cselect_b32 s23, s12, s55
	s_add_i32 s25, s8, 0
	v_cndmask_b32_e64 v2, 0, 1, s[4:5]
	v_and_b32_e32 v1, 63, v0
	s_mov_b32 s9, 0
	s_mov_b32 s24, 0x10000
	s_add_i32 s25, s25, 0x10000
	s_and_b64 s[10:11], s[10:11], s[6:7]
	v_cmp_ne_u32_e64 s[4:5], 1, v2
	v_mov_b32_e32 v3, 0
	s_movk_i32 s26, 0x2000
	s_movk_i32 s27, 0x4000
	s_movk_i32 s28, 0x6000
	s_mov_b32 s29, 0x8000
	s_mov_b32 s30, 0xa000
	s_mov_b32 s31, 0xe000
	s_mov_b32 s34, 0x14000
	s_mov_b32 s35, 0x16000
	s_mov_b32 s36, 0x18000
	s_mov_b32 s37, 0x1a000
	s_mov_b32 s38, 0x1c000
	s_mov_b32 s39, 0x1e000
	s_mov_b32 s41, 0x20000
	s_mov_b32 s42, 0x22000
	s_mov_b32 s43, 0x24000
	s_mov_b32 s45, 0x26000
	s_mov_b32 s46, 0x28000
	s_mov_b32 s47, 0x2a000
	s_mov_b32 s49, 0x2c000
	s_mov_b32 s57, 0x2e000
	s_mov_b32 s58, 0x30000
	s_mov_b32 s59, 0x32000
	s_mov_b32 s72, 0x34000
	s_mov_b32 s73, 0x36000
	s_mov_b32 s78, 0x38000
	s_mov_b32 s79, 0x3a000
	s_mov_b32 s84, 0x3c000
	s_mov_b32 s85, 0x3e000
	s_movk_i32 s86, 0x84
	s_branch .LBB0_2352

.LBB0_2670:
	s_cmp_lt_i32 s61, 39
	s_cbranch_scc1 .LBB0_3322
	s_cmp_gt_i32 s60, 38
	s_cbranch_scc1 .LBB0_2740
	v_writelane_b32 v129, s3, 0
	v_writelane_b32 v129, s4, 1
	v_writelane_b32 v129, s5, 2
	v_writelane_b32 v129, s6, 3
	v_writelane_b32 v129, s7, 4
	v_writelane_b32 v129, s8, 5
	v_writelane_b32 v129, s9, 6
	v_writelane_b32 v129, s10, 7
	v_writelane_b32 v129, s11, 8
	v_writelane_b32 v129, s12, 9
	v_writelane_b32 v129, s13, 10
	v_writelane_b32 v129, s14, 11
	v_writelane_b32 v129, s15, 12
	v_writelane_b32 v129, s16, 13
	v_writelane_b32 v129, s17, 14
	v_writelane_b32 v129, s18, 15
	v_writelane_b32 v129, s19, 16
	v_writelane_b32 v129, s20, 17
	v_writelane_b32 v129, s21, 18
	v_writelane_b32 v129, s22, 19
	v_writelane_b32 v129, s23, 20
	v_writelane_b32 v129, s24, 21
	v_writelane_b32 v129, s25, 22
	v_writelane_b32 v129, s26, 23
	v_writelane_b32 v129, s27, 24
	v_writelane_b32 v129, s28, 25
	v_writelane_b32 v129, s29, 26
	v_writelane_b32 v129, s30, 27
	v_writelane_b32 v129, s31, 28
	v_writelane_b32 v129, s33, 29
	v_writelane_b32 v129, s34, 30
	v_writelane_b32 v129, s35, 31
	v_writelane_b32 v129, s36, 32
	v_writelane_b32 v129, s37, 33
	v_writelane_b32 v129, s38, 34
	v_writelane_b32 v129, s39, 35
	v_writelane_b32 v129, s41, 36
	v_writelane_b32 v129, s42, 37
	v_writelane_b32 v129, s43, 38
	v_writelane_b32 v129, s45, 39
	v_writelane_b32 v129, s46, 40
	v_writelane_b32 v129, s47, 41
	v_writelane_b32 v129, s49, 42
	v_writelane_b32 v129, s57, 43
	v_writelane_b32 v129, s58, 44
	v_writelane_b32 v129, s59, 45
	v_writelane_b32 v129, s72, 46
	v_writelane_b32 v129, s73, 47
	v_writelane_b32 v129, s76, 48
	v_writelane_b32 v129, s77, 49
	v_writelane_b32 v129, s78, 50
	v_writelane_b32 v129, s79, 51
	v_writelane_b32 v129, s80, 52
	v_writelane_b32 v129, s81, 53
	v_writelane_b32 v129, s84, 54
	v_writelane_b32 v129, s85, 55
	v_writelane_b32 v129, s86, 56
	v_writelane_b32 v129, s87, 57
	v_writelane_b32 v129, s88, 58
	v_writelane_b32 v129, s89, 59
	v_writelane_b32 v129, s90, 60
	v_writelane_b32 v129, s91, 61
	v_writelane_b32 v129, s92, 62
	v_writelane_b32 v129, s93, 63
	s_cmpk_lt_u32 s2, 0x60
	s_cselect_b64 s[4:5], -1, 0
	s_cmpk_gt_u32 s2, 0x5f
	s_cselect_b64 s[10:11], -1, 0
	s_mov_b32 s3, 0x12900
	s_and_b64 s[6:7], s[10:11], exec
	s_cselect_b32 s12, s3, 0x13d00
	s_mov_b32 s3, 0x13d00
	s_cselect_b32 s13, 0x13d00, s3
	s_add_i32 s14, s54, 0xc000
	s_cmpk_eq_i32 s56, 0x100
	s_cselect_b64 s[6:7], -1, 0
	s_and_b64 s[8:9], s[6:7], exec
	s_cselect_b32 s18, s13, 0
	s_cselect_b32 s19, s12, s14
	s_mov_b32 s3, 0xc000
	s_cmp_ge_u32 s19, s18
	s_mov_b32 s20, 0x12000
	s_waitcnt vmcnt(0)
	s_barrier
	s_cbranch_scc1 .Lcq2_end
	v_readlane_b32 s8, v255, 7
	s_sub_i32 s8, s8, 0x300
	v_readlane_b32 s13, v255, 6
	s_add_i32 s21, s13, s8
	s_lshl_b32 s22, s21, 1
	s_movk_i32 s12, 0xa00
	s_and_b64 s[8:9], s[10:11], exec
	s_cselect_b32 s12, s12, 0x400
	s_and_b64 s[8:9], s[6:7], exec
	s_mul_i32 s8, s13, 0x2200
	s_cselect_b32 s23, s12, s55
	s_add_i32 s25, s8, 0
	v_cndmask_b32_e64 v2, 0, 1, s[4:5]
	v_and_b32_e32 v1, 63, v0
	s_mov_b32 s9, 0
	s_mov_b32 s24, 0x10000
	s_add_i32 s25, s25, 0x10000
	s_and_b64 s[10:11], s[10:11], s[6:7]
	v_cmp_ne_u32_e64 s[4:5], 1, v2
	v_mov_b32_e32 v3, 0
	s_movk_i32 s26, 0x2000
	s_movk_i32 s27, 0x4000
	s_movk_i32 s28, 0x6000
	s_mov_b32 s29, 0x8000
	s_mov_b32 s30, 0xa000
	s_mov_b32 s31, 0xe000
	s_mov_b32 s34, 0x14000
	s_mov_b32 s35, 0x16000
	s_mov_b32 s36, 0x18000
	s_mov_b32 s37, 0x1a000
	s_mov_b32 s38, 0x1c000
	s_mov_b32 s39, 0x1e000
	s_mov_b32 s41, 0x20000
	s_mov_b32 s42, 0x22000
	s_mov_b32 s43, 0x24000
	s_mov_b32 s45, 0x26000
	s_mov_b32 s46, 0x28000
	s_mov_b32 s47, 0x2a000
	s_mov_b32 s49, 0x2c000
	s_mov_b32 s57, 0x2e000
	s_mov_b32 s58, 0x30000
	s_mov_b32 s59, 0x32000
	s_mov_b32 s72, 0x34000
	s_mov_b32 s73, 0x36000
	s_mov_b32 s78, 0x38000
	s_mov_b32 s79, 0x3a000
	s_mov_b32 s84, 0x3c000
	s_mov_b32 s85, 0x3e000
	s_movk_i32 s86, 0x84
	s_branch .Lcq2_2352

.LBB0_2807:
	s_cmp_gt_i32 s60, 42
	s_cselect_b64 s[4:5], -1, 0
	s_cmp_lt_i32 s61, 43
	s_cselect_b64 s[6:7], -1, 0
	s_or_b64 s[4:5], s[4:5], s[6:7]
	s_and_b64 vcc, exec, s[4:5]
	s_cbranch_vccnz .LBB0_2883
	v_writelane_b32 v129, s3, 0
	v_writelane_b32 v129, s4, 1
	v_writelane_b32 v129, s5, 2
	v_writelane_b32 v129, s6, 3
	v_writelane_b32 v129, s7, 4
	v_writelane_b32 v129, s8, 5
	v_writelane_b32 v129, s9, 6
	v_writelane_b32 v129, s10, 7
	v_writelane_b32 v129, s11, 8
	v_writelane_b32 v129, s12, 9
	v_writelane_b32 v129, s13, 10
	v_writelane_b32 v129, s14, 11
	v_writelane_b32 v129, s15, 12
	v_writelane_b32 v129, s16, 13
	v_writelane_b32 v129, s17, 14
	v_writelane_b32 v129, s18, 15
	v_writelane_b32 v129, s19, 16
	v_writelane_b32 v129, s20, 17
	v_writelane_b32 v129, s21, 18
	v_writelane_b32 v129, s22, 19
	v_writelane_b32 v129, s23, 20
	v_writelane_b32 v129, s24, 21
	v_writelane_b32 v129, s25, 22
	v_writelane_b32 v129, s26, 23
	v_writelane_b32 v129, s27, 24
	v_writelane_b32 v129, s28, 25
	v_writelane_b32 v129, s29, 26
	v_writelane_b32 v129, s30, 27
	v_writelane_b32 v129, s31, 28
	v_writelane_b32 v129, s33, 29
	v_writelane_b32 v129, s34, 30
	v_writelane_b32 v129, s35, 31
	v_writelane_b32 v129, s36, 32
	v_writelane_b32 v129, s37, 33
	v_writelane_b32 v129, s38, 34
	v_writelane_b32 v129, s39, 35
	v_writelane_b32 v129, s41, 36
	v_writelane_b32 v129, s42, 37
	v_writelane_b32 v129, s43, 38
	v_writelane_b32 v129, s45, 39
	v_writelane_b32 v129, s46, 40
	v_writelane_b32 v129, s47, 41
	v_writelane_b32 v129, s49, 42
	v_writelane_b32 v129, s57, 43
	v_writelane_b32 v129, s58, 44
	v_writelane_b32 v129, s59, 45
	v_writelane_b32 v129, s72, 46
	v_writelane_b32 v129, s73, 47
	v_writelane_b32 v129, s76, 48
	v_writelane_b32 v129, s77, 49
	v_writelane_b32 v129, s78, 50
	v_writelane_b32 v129, s79, 51
	v_writelane_b32 v129, s80, 52
	v_writelane_b32 v129, s81, 53
	v_writelane_b32 v129, s84, 54
	v_writelane_b32 v129, s85, 55
	v_writelane_b32 v129, s86, 56
	v_writelane_b32 v129, s87, 57
	v_writelane_b32 v129, s88, 58
	v_writelane_b32 v129, s89, 59
	v_writelane_b32 v129, s90, 60
	v_writelane_b32 v129, s91, 61
	v_writelane_b32 v129, s92, 62
	v_writelane_b32 v129, s93, 63
	s_cmpk_lt_u32 s2, 0x20
	s_cselect_b64 s[4:5], -1, 0
	s_cmpk_gt_u32 s2, 0x1f
	s_cselect_b64 s[10:11], -1, 0
	s_mov_b32 s3, 0x13d00
	s_and_b64 s[6:7], s[10:11], exec
	s_cselect_b32 s12, s3, 0x15900
	s_mov_b32 s3, 0x15900
	s_cselect_b32 s13, 0x15900, s3
	s_add_i32 s14, s54, 0xc000
	s_cmpk_eq_i32 s56, 0x100
	s_cselect_b64 s[6:7], -1, 0
	s_and_b64 s[8:9], s[6:7], exec
	s_cselect_b32 s18, s13, 0
	s_cselect_b32 s19, s12, s14
	s_mov_b32 s3, 0xc000
	s_cmp_ge_u32 s19, s18
	s_mov_b32 s20, 0x12000
	s_waitcnt vmcnt(0)
	s_barrier
	s_cbranch_scc1 .Lcq3_end
	v_readlane_b32 s8, v255, 7
	s_sub_i32 s8, s8, 0x100
	v_readlane_b32 s13, v255, 6
	s_add_i32 s21, s13, s8
	s_lshl_b32 s22, s21, 1
	s_movk_i32 s12, 0xe00
	s_and_b64 s[8:9], s[10:11], exec
	s_cselect_b32 s12, s12, 0x400
	s_and_b64 s[8:9], s[6:7], exec
	s_mul_i32 s8, s13, 0x2200
	s_cselect_b32 s23, s12, s55
	s_add_i32 s25, s8, 0
	v_cndmask_b32_e64 v2, 0, 1, s[4:5]
	v_and_b32_e32 v1, 63, v0
	s_mov_b32 s9, 0
	s_mov_b32 s24, 0x10000
	s_add_i32 s25, s25, 0x10000
	s_and_b64 s[10:11], s[10:11], s[6:7]
	v_cmp_ne_u32_e64 s[4:5], 1, v2
	v_mov_b32_e32 v3, 0
	s_movk_i32 s26, 0x2000
	s_movk_i32 s27, 0x4000
	s_movk_i32 s28, 0x6000
	s_mov_b32 s29, 0x8000
	s_mov_b32 s30, 0xa000
	s_mov_b32 s31, 0xe000
	s_mov_b32 s34, 0x14000
	s_mov_b32 s35, 0x16000
	s_mov_b32 s36, 0x18000
	s_mov_b32 s37, 0x1a000
	s_mov_b32 s38, 0x1c000
	s_mov_b32 s39, 0x1e000
	s_mov_b32 s41, 0x20000
	s_mov_b32 s42, 0x22000
	s_mov_b32 s43, 0x24000
	s_mov_b32 s45, 0x26000
	s_mov_b32 s46, 0x28000
	s_mov_b32 s47, 0x2a000
	s_mov_b32 s49, 0x2c000
	s_mov_b32 s57, 0x2e000
	s_mov_b32 s58, 0x30000
	s_mov_b32 s59, 0x32000
	s_mov_b32 s72, 0x34000
	s_mov_b32 s73, 0x36000
	s_mov_b32 s78, 0x38000
	s_mov_b32 s79, 0x3a000
	s_mov_b32 s84, 0x3c000
	s_mov_b32 s85, 0x3e000
	s_movk_i32 s86, 0x84
	s_branch .Lcq3_2352

.LBB0_3025:
	s_cmpk_lt_u32 s2, 0x80
	s_cselect_b64 s[4:5], -1, 0
	s_cmpk_gt_u32 s2, 0x7f
	s_cselect_b64 s[10:11], -1, 0
	s_mov_b32 s3, 0x15900
	s_and_b64 s[6:7], s[10:11], exec
	s_cselect_b32 s12, s3, 0x17900
	s_add_i32 s13, s54, 0x12000
	s_cmpk_eq_i32 s56, 0x100
	s_cselect_b64 s[6:7], -1, 0
	s_and_b64 s[8:9], s[6:7], exec
	s_cselect_b32 s18, s12, s13
	s_and_b64 s[8:9], s[10:11], s[6:7]
	s_mov_b32 s19, 0x18000
	s_and_b64 s[12:13], s[8:9], exec
	s_cselect_b32 s20, 0x17900, s19
	s_mov_b32 s3, 0x12000
	s_cmp_ge_u32 s18, s20
	s_waitcnt vmcnt(0)
	s_barrier
	s_cbranch_scc1 .LBB0_3040
	v_readlane_b32 s12, v255, 7
	s_and_b32 s12, s12, 0x3f8
	v_readlane_b32 s13, v255, 6
	s_add_i32 s21, s13, s12
	s_lshl_b32 s22, s21, 1
	s_movk_i32 s12, 0x800
	s_and_b64 s[10:11], s[10:11], exec
	s_cselect_b32 s12, s12, 0x400
	s_and_b64 s[10:11], s[6:7], exec
	s_mul_i32 s10, s13, 0x2200
	s_cselect_b32 s23, s12, s55
	s_add_i32 s25, s10, 0
	v_cndmask_b32_e64 v2, 0, 1, s[4:5]
	s_mov_b32 s11, 0
	s_mov_b32 s24, 0x10000
	s_add_i32 s25, s25, 0x10000
	v_cmp_ne_u32_e64 s[4:5], 1, v2
	v_mov_b32_e32 v3, 0
	s_movk_i32 s26, 0x2000
	s_movk_i32 s27, 0x4000
	s_movk_i32 s28, 0x6000
	s_mov_b32 s29, 0x8000
	s_mov_b32 s30, 0xa000
	s_mov_b32 s31, 0xc000
	s_mov_b32 s34, 0xe000
	s_mov_b32 s35, 0x14000
	s_mov_b32 s36, 0x16000
	s_mov_b32 s37, 0x1a000
	s_mov_b32 s38, 0x1c000
	s_mov_b32 s39, 0x1e000
	s_mov_b32 s41, 0x20000
	s_mov_b32 s42, 0x22000
	s_mov_b32 s43, 0x24000
	s_mov_b32 s45, 0x26000
	s_mov_b32 s46, 0x28000
	s_mov_b32 s47, 0x2a000
	s_mov_b32 s50, 0x2c000
	s_mov_b32 s51, 0x2e000
	s_mov_b32 s57, 0x30000
	s_mov_b32 s58, 0x32000
	s_mov_b32 s59, 0x34000
	s_mov_b32 s72, 0x36000
	s_mov_b32 s73, 0x38000
	s_mov_b32 s76, 0x3a000
	s_mov_b32 s77, 0x3c000
	s_mov_b32 s78, 0x3e000
	s_movk_i32 s79, 0x84
	s_movk_i32 s80, 0xc8
	s_branch .LBB0_3028
